# v110 + next-tile work-queue prefetch in the out-proj GEMM too (same scheme as in-proj / MLP1 / MLP2)
# speedup vs baseline: 1.0043x; 1.0015x over previous
.LBB0_954:
	s_getreg_b32 s0, hwreg(HW_REG_XCC_ID, 0, 4)
	s_and_b32 s25, s0, 7
	s_add_i32 s10, s42, 8
	v_readlane_b32 s0, v254, 62
	s_ashr_i32 s11, s10, 31
	s_lshl_b32 s0, s0, 10
	s_add_u32 s0, s30, s0
	v_readlane_b32 s40, v254, 52
	s_addc_u32 s1, s31, 0
	v_readlane_b32 s41, v254, 53
	s_and_b64 s[40:41], s[40:41], exec
	s_cselect_b32 s34, 0x1000, s21
	s_lshl_b64 s[10:11], s[10:11], 2
	v_readlane_b32 s40, v252, 55
	v_readlane_b32 s41, v252, 56
	s_add_u32 s10, s40, s10
	s_addc_u32 s11, s41, s11
	v_readlane_b32 s40, v252, 19
	v_readlane_b32 s41, v252, 20
	s_add_u32 s40, s40, s34
	s_addc_u32 s41, s41, 0
	v_mov_b32_e32 v126, 0
	v_mov_b32_e32 v16, s25
	s_mov_b32 s99, 0
	s_branch .LBB0_956
.LBB0_955:
	v_readfirstlane_b32 s99, v195
	s_mov_b64 s[100:101], exec
	s_cmp_lg_u32 s99, 0
	s_cbranch_scc1 .Lpfa_skip_op
	s_mov_b64 exec, 1
	v_lshl_add_u64 v[248:249], v[16:17], 2, s[10:11]
	global_atomic_add v248, v[248:249], v229, off sc0
	s_mov_b64 exec, s[100:101]
.Lpfa_skip_op:
	s_mov_b32 s99, 1
	v_or_b32_e32 v0, s34, v129
	v_and_b32_e32 v1, 64, v128
	v_add_u32_e32 v0, v0, v130
	v_lshlrev_b32_e32 v2, 2, v127
	v_or3_b32 v6, v2, v1, s25
	v_ashrrev_i32_e32 v1, 31, v0
	v_lshlrev_b64 v[2:3], 11, v[0:1]
	v_lshl_add_u64 v[2:3], s[6:7], 0, v[2:3]
	v_lshlrev_b32_e32 v6, 1, v6
	v_and_b32_e32 v9, 1, v127
	v_mul_u32_u24_e32 v9, 24, v9
	v_add_u32_e32 v6, v6, v9
	v_mov_b32_e32 v7, v17
	v_cvt_pk_bf16_f32 v160, v46, v47
	v_cvt_pk_bf16_f32 v161, v48, v49
	v_cvt_pk_bf16_f32 v162, v42, v43
	v_cvt_pk_bf16_f32 v163, v44, v45
	v_cvt_pk_bf16_f32 v164, v34, v35
	v_cvt_pk_bf16_f32 v165, v36, v37
	v_cvt_pk_bf16_f32 v166, v22, v23
	v_cvt_pk_bf16_f32 v167, v24, v25
	v_lshl_add_u64 v[2:3], v[2:3], 0, v[6:7]
	s_nop 1
	v_permlane16_swap_b32 v160, v162
	v_permlane16_swap_b32 v161, v163
	v_permlane16_swap_b32 v164, v166
	v_permlane16_swap_b32 v165, v167
	s_nop 1
	global_store_dwordx4 v[2:3], v[160:163], off sc1
	global_store_dwordx4 v[2:3], v[164:167], off offset:64 sc1
	v_cvt_pk_bf16_f32 v168, v30, v31
	v_cvt_pk_bf16_f32 v169, v32, v33
	v_cvt_pk_bf16_f32 v170, v18, v19
	v_cvt_pk_bf16_f32 v171, v20, v21
	v_cvt_pk_bf16_f32 v172, v38, v39
	v_cvt_pk_bf16_f32 v173, v40, v41
	v_cvt_pk_bf16_f32 v174, v26, v27
	v_cvt_pk_bf16_f32 v175, v28, v29
	v_or_b32_e32 v2, 16, v0
	v_ashrrev_i32_e32 v3, 31, v2
	v_lshlrev_b64 v[2:3], 11, v[2:3]
	v_lshl_add_u64 v[2:3], s[6:7], 0, v[2:3]
	v_lshl_add_u64 v[2:3], v[2:3], 0, v[6:7]
	s_nop 1
	v_permlane16_swap_b32 v168, v170
	v_permlane16_swap_b32 v169, v171
	v_permlane16_swap_b32 v172, v174
	v_permlane16_swap_b32 v173, v175
	s_nop 1
	global_store_dwordx4 v[2:3], v[168:171], off sc1
	global_store_dwordx4 v[2:3], v[172:175], off offset:64 sc1
	v_cvt_pk_bf16_f32 v160, v70, v71
	v_cvt_pk_bf16_f32 v161, v72, v73
	v_cvt_pk_bf16_f32 v162, v66, v67
	v_cvt_pk_bf16_f32 v163, v68, v69
	v_cvt_pk_bf16_f32 v164, v62, v63
	v_cvt_pk_bf16_f32 v165, v64, v65
	v_cvt_pk_bf16_f32 v166, v58, v59
	v_cvt_pk_bf16_f32 v167, v60, v61
	v_or_b32_e32 v2, 32, v0
	v_ashrrev_i32_e32 v3, 31, v2
	v_lshlrev_b64 v[2:3], 11, v[2:3]
	v_lshl_add_u64 v[2:3], s[6:7], 0, v[2:3]
	v_lshl_add_u64 v[2:3], v[2:3], 0, v[6:7]
	v_or_b32_e32 v0, 48, v0
	v_ashrrev_i32_e32 v1, 31, v0
	v_lshlrev_b64 v[0:1], 11, v[0:1]
	v_lshl_add_u64 v[0:1], s[6:7], 0, v[0:1]
	s_nop 1
	v_permlane16_swap_b32 v160, v162
	v_permlane16_swap_b32 v161, v163
	v_permlane16_swap_b32 v164, v166
	v_permlane16_swap_b32 v165, v167
	s_nop 1
	global_store_dwordx4 v[2:3], v[160:163], off sc1
	global_store_dwordx4 v[2:3], v[164:167], off offset:64 sc1
	v_cvt_pk_bf16_f32 v168, v78, v79
	v_cvt_pk_bf16_f32 v169, v80, v81
	v_cvt_pk_bf16_f32 v170, v74, v75
	v_cvt_pk_bf16_f32 v171, v76, v77
	v_cvt_pk_bf16_f32 v172, v82, v83
	v_cvt_pk_bf16_f32 v173, v84, v85
	v_cvt_pk_bf16_f32 v174, v86, v87
	v_cvt_pk_bf16_f32 v175, v88, v89
	v_lshl_add_u64 v[0:1], v[0:1], 0, v[6:7]
	s_nop 1
	v_permlane16_swap_b32 v168, v170
	v_permlane16_swap_b32 v169, v171
	v_permlane16_swap_b32 v172, v174
	v_permlane16_swap_b32 v173, v175
	s_nop 1
	global_store_dwordx4 v[0:1], v[168:171], off sc1
	global_store_dwordx4 v[0:1], v[172:175], off offset:64 sc1

.LBB0_960:
	v_cmp_gt_i32_e32 vcc, 8, v126
	s_or_b64 s[48:49], s[48:49], exec
	s_and_saveexec_b64 s[50:51], vcc
	s_cbranch_execz .LBB0_959
	s_waitcnt vmcnt(0)
	s_cmp_eq_u32 s99, 1
	s_cbranch_scc0 .Lpf_none_op
	s_mov_b32 s99, 0
	s_waitcnt vmcnt(0)
	v_mov_b32_e32 v1, v248
	s_branch .Lpf_have_op
.Lpf_none_op:
	v_lshl_add_u64 v[2:3], v[16:17], 2, s[10:11]
	global_atomic_add v1, v[2:3], v229, off sc0
.Lpf_have_op:
	s_movk_i32 s25, 0x90
	s_waitcnt vmcnt(0)
	v_cmp_gt_i32_e32 vcc, s25, v1
	s_and_saveexec_b64 s[52:53], vcc
	s_xor_b64 s[52:53], exec, s[52:53]
	v_ashrrev_i32_e32 v0, 31, v1
	v_lshrrev_b32_e32 v0, 29, v0
	v_add_u32_e32 v4, v1, v0
	v_lshrrev_b32_e32 v0, 3, v4
	v_mad_u64_u32 v[2:3], s[54:55], v16, 18, v[0:1]
	v_and_b32_e32 v0, -8, v4
	v_sub_u32_e32 v0, v1, v0
	v_lshl_or_b32 v0, v2, 6, v0
	s_andn2_saveexec_b64 s[52:53], s[52:53]
	s_cbranch_execz .LBB0_958
	v_add_u32_e32 v1, 1, v16
	v_and_b32_e32 v16, 7, v1
	v_add_u32_e32 v126, 1, v126
	s_branch .LBB0_958
